# lever 9/6.4 (segment head): left-of-diagonal attention bodies: ALiBi C init moved to the end of the previous body (before the tile barrier) so the post-barrier segment opens with K reads + MFMA
# baseline (speedup 1.0000x reference)
; template <bool STORE> __device__ __forceinline__ void attn_unit(LAS unsigned char* lds, bf16_t* Q, const bf16_t* Kg, const bf16_t* VT, const float* subg, float lam, float outscale, int unit, const int wave_s) {
;     ...
;     f32x16 o[4]; o[0] = f32x16{}; o[1] = f32x16{}; o[2] = f32x16{}; o[3] = f32x16{};
;     float mref = sself + 6.0f, lsum = 0.f;
;     const int koff = q * 256 + (((map * 8 + hi) ^ (q & 15)) << 4), voff = AT_VOFF + q * 128 + ((hi ^ ((q >> 1) & 7)) << 4);
;     const float qposf = (float)(qrow0 + q - 4 * hi);
;     f32x16 x0, x1, n0, n1;
.LBB0_581:
	v_lshlrev_b32_e32 v0, 7, v3
	v_lshrrev_b32_e32 v3, 1, v219
	v_bitop3_b32 v2, v2, v3, 7 bitop3:0x78
	s_lshr_b32 s16, s12, 6
	v_lshl_or_b32 v215, v2, 4, v0
	s_waitcnt lgkmcnt(0)
	s_barrier
	s_cmpk_lt_u32 s12, 0xc0
	s_mov_b64 s[12:13], 0xf80
	v_or_b32_e32 v214, 0x10000, v215
	v_lshl_add_u64 v[174:175], v[182:183], 0, s[12:13]
	v_add_f32_e32 v167, v166, v166
	v_add_u32_e32 v204, 0, v214
	v_lshl_add_u64 v[176:177], v[172:173], 1, v[174:175]
	v_fma_f32 v185, 2.0, v166, v167
	v_xor_b32_e32 v203, 0x10020, v215
	v_xor_b32_e32 v202, 0x10040, v215
	v_xor_b32_e32 v179, 0x10060, v215
	s_cbranch_scc1 .LBB0_605
	v_xor_b32_e32 v0, 0x10020, v215
	v_readlane_b32 s12, v253, 23
	v_mov_b32_e32 v184, v166
	v_mov_b32_e32 v2, v167
	v_mov_b32_e32 v3, v185
	v_add_u32_e32 v220, 0, v0
	v_xor_b32_e32 v0, 0x10040, v215
	s_add_i32 s12, s34, s12
	v_add_f32_e32 v186, v184, v2
	v_add_f32_e32 v187, v185, v3
	v_add_u32_e32 v221, 0, v0
	v_xor_b32_e32 v0, 0x10060, v215
	v_add_u32_e32 v2, s12, v216
	v_add_u32_e32 v222, 0, v0
	v_ashrrev_i32_e32 v3, 31, v2
	v_add_u32_e32 v0, s19, v218
	v_lshlrev_b64 v[188:189], 11, v[2:3]
	v_lshlrev_b64 v[2:3], 15, v[0:1]
	v_lshl_or_b32 v2, v217, 4, v2
	v_mov_b32_e32 v14, v1
	v_mov_b32_e32 v15, v1
	v_add_f32_e32 v168, v187, v187
	s_and_b32 s12, s18, 0x700
	v_lshl_add_u64 v[190:191], s[34:35], 1, v[2:3]
	v_mov_b32_e32 v0, v1
	v_mov_b32_e32 v2, v1
	v_mov_b32_e32 v3, v1
	v_mov_b32_e32 v4, v1
	v_mov_b32_e32 v5, v1
	v_mov_b32_e32 v6, v1
	v_mov_b32_e32 v7, v1
	v_mov_b32_e32 v8, v1
	v_mov_b32_e32 v9, v1
	v_mov_b32_e32 v10, v1
	v_mov_b32_e32 v11, v1
	v_mov_b32_e32 v12, v1
	v_mov_b32_e32 v13, v1
	v_mov_b64_e32 v[78:79], v[14:15]
	v_mov_b64_e32 v[62:63], v[14:15]
	v_mov_b64_e32 v[46:47], v[14:15]
	v_mov_b64_e32 v[30:31], v[14:15]
	v_fmac_f32_e32 v168, 2.0, v187
	v_or3_b32 v188, v188, s12, v178
	s_mov_b32 s20, 0
	v_mov_b32_e32 v184, 0
	s_mov_b32 s21, 0x14000
	s_movk_i32 s28, 0x80
	v_mov_b64_e32 v[76:77], v[12:13]
	v_mov_b64_e32 v[74:75], v[10:11]
	v_mov_b64_e32 v[72:73], v[8:9]
	v_mov_b64_e32 v[70:71], v[6:7]
	v_mov_b64_e32 v[68:69], v[4:5]
	v_mov_b64_e32 v[66:67], v[2:3]
	v_mov_b64_e32 v[64:65], v[0:1]
	v_mov_b64_e32 v[60:61], v[12:13]
	v_mov_b64_e32 v[58:59], v[10:11]
	v_mov_b64_e32 v[56:57], v[8:9]
	v_mov_b64_e32 v[54:55], v[6:7]
	v_mov_b64_e32 v[52:53], v[4:5]
	v_mov_b64_e32 v[50:51], v[2:3]
	v_mov_b64_e32 v[48:49], v[0:1]
	v_mov_b64_e32 v[44:45], v[12:13]
	v_mov_b64_e32 v[42:43], v[10:11]
	v_mov_b64_e32 v[40:41], v[8:9]
	v_mov_b64_e32 v[38:39], v[6:7]
	v_mov_b64_e32 v[36:37], v[4:5]
	v_mov_b64_e32 v[34:35], v[2:3]
	v_mov_b64_e32 v[32:33], v[0:1]
	v_mov_b64_e32 v[28:29], v[12:13]
	v_mov_b64_e32 v[26:27], v[10:11]
	v_mov_b64_e32 v[24:25], v[8:9]
	v_mov_b64_e32 v[22:23], v[6:7]
	v_mov_b64_e32 v[20:21], v[4:5]
	v_mov_b64_e32 v[18:19], v[2:3]
	v_mov_b64_e32 v[16:17], v[0:1]
	s_sub_i32 s30, s28, 64
	v_cvt_f32_u32_e32 v112, s30
	v_sub_f32_e32 v112, v112, v205
	v_fma_f32 v112, v166, v112, -v169
	v_add_f32_e32 v128, v168, v112
	v_add_f32_e32 v129, v166, v128
	v_add_f32_e32 v130, v167, v128
	v_add_f32_e32 v131, v186, v128
	v_add_f32_e32 v132, v187, v128
	v_add_f32_e32 v133, v166, v132
	v_add_f32_e32 v134, v167, v132
	v_add_f32_e32 v135, v186, v132
	v_add_f32_e32 v136, v187, v132
	v_add_f32_e32 v137, v166, v136
	v_add_f32_e32 v138, v167, v136
	v_add_f32_e32 v139, v186, v136
	v_add_f32_e32 v140, v187, v136
	v_add_f32_e32 v141, v166, v140
	v_add_f32_e32 v142, v167, v140
	v_add_f32_e32 v143, v186, v140
	v_add_f32_e32 v113, v166, v112
	v_add_f32_e32 v114, v167, v112
	v_add_f32_e32 v115, v186, v112
	v_add_f32_e32 v116, v187, v112
	v_add_f32_e32 v117, v166, v116
	v_add_f32_e32 v118, v167, v116
	v_add_f32_e32 v119, v186, v116
	v_add_f32_e32 v120, v187, v116
	v_add_f32_e32 v121, v166, v120
	v_add_f32_e32 v122, v167, v120
	v_add_f32_e32 v123, v186, v120
	v_add_f32_e32 v124, v187, v120
	v_add_f32_e32 v125, v166, v124
	v_add_f32_e32 v126, v167, v124
	v_add_f32_e32 v127, v186, v124

.LBB0_589:
	s_add_i32 s30, s21, 0xffff0000
	s_and_b32 s30, s30, 0xc000
	s_add_i32 s42, s30, 0
	v_add_u32_e32 v0, s42, v210
	s_sub_i32 s43, s28, 64
	ds_read_b128 v[6:9], v0
	ds_read_b128 v[10:13], v0 offset:8192
	v_add_u32_e32 v14, s42, v211
	ds_read_b128 v[224:227], v14
	ds_read_b128 v[228:231], v14 offset:8192
	s_add_i32 s36, s21, 0xfffec000
	s_waitcnt lgkmcnt(2)
	v_mfma_f32_32x32x16_bf16 v[128:143], v[10:13], v[144:147], v[128:143]
	v_add_u32_e32 v0, s42, v212
	s_and_b32 s36, s36, 0x8000
	v_exp_f32_e32 v96, v96
	v_exp_f32_e32 v14, v97
	v_exp_f32_e32 v80, v80
	v_exp_f32_e32 v98, v98
	v_exp_f32_e32 v82, v82
	v_mfma_f32_32x32x16_bf16 v[112:127], v[6:9], v[144:147], v[112:127]
	ds_read_b128 v[6:9], v0
	ds_read_b128 v[10:13], v0 offset:8192
	v_add_u32_e32 v0, s42, v213
	v_exp_f32_e32 v248, v99
	v_exp_f32_e32 v250, v83
	v_exp_f32_e32 v83, v84
	v_exp_f32_e32 v84, v86
	v_exp_f32_e32 v196, v103
	s_waitcnt lgkmcnt(3)
	v_mfma_f32_32x32x16_bf16 v[112:127], v[224:227], v[148:151], v[112:127]
	ds_read_b128 v[224:227], v0
	ds_read_b128 v[232:235], v0 offset:8192
	v_add_u32_e32 v0, s36, v204
	ds_read_b128 v[236:239], v0
	ds_read_b128 v[240:243], v0 offset:4096
	v_exp_f32_e32 v86, v106
	v_exp_f32_e32 v198, v105
	v_exp_f32_e32 v106, v89
	v_exp_f32_e32 v164, v107
	s_waitcnt lgkmcnt(6)
	v_mfma_f32_32x32x16_bf16 v[128:143], v[228:231], v[148:151], v[128:143]
	ds_read_b128 v[228:231], v0 offset:8192
	ds_read_b128 v[244:247], v0 offset:12288
	v_exp_f32_e32 v0, v81
	v_exp_f32_e32 v81, v104
	v_exp_f32_e32 v104, v87
	v_exp_f32_e32 v87, v90
	v_exp_f32_e32 v160, v91
	v_exp_f32_e32 v89, v92
	s_waitcnt lgkmcnt(7)
	v_mfma_f32_32x32x16_bf16 v[112:127], v[6:9], v[152:155], v[112:127]
	v_exp_f32_e32 v8, v100
	v_exp_f32_e32 v9, v102
	v_exp_f32_e32 v90, v110
	v_exp_f32_e32 v91, v94
	v_exp_f32_e32 v162, v109
	v_exp_f32_e32 v200, v111
	v_exp_f32_e32 v110, v95
	s_waitcnt lgkmcnt(6)
	v_mfma_f32_32x32x16_bf16 v[128:143], v[10:13], v[152:155], v[128:143]
	v_cvt_pk_bf16_f32 v6, v96, v14
	v_add_f32_e32 v15, v96, v80
	v_add_f32_e32 v249, v98, v82
	v_add_f32_e32 v197, v9, v84
	v_add_f32_e32 v165, v86, v87
	v_add_f32_e32 v201, v90, v91
	v_cvt_pk_bf16_f32 v7, v98, v248
	s_waitcnt lgkmcnt(5)
	v_mfma_f32_32x32x16_bf16 v[112:127], v[224:227], v[156:159], v[112:127]
	v_exp_f32_e32 v224, v101
	v_exp_f32_e32 v226, v85
	v_exp_f32_e32 v85, v88
	v_exp_f32_e32 v88, v108
	v_exp_f32_e32 v108, v93
	v_add_f32_e32 v225, v8, v83
	v_add_f32_e32 v199, v81, v85
	s_waitcnt lgkmcnt(4)
	v_mfma_f32_32x32x16_bf16 v[128:143], v[232:235], v[156:159], v[128:143]
	v_add_f32_e32 v163, v88, v89
	v_cvt_pk_bf16_f32 v8, v8, v224
	v_cvt_pk_bf16_f32 v9, v9, v196
	v_cvt_pk_bf16_f32 v10, v81, v198
	v_cvt_pk_bf16_f32 v11, v86, v164
	v_cvt_pk_bf16_f32 v12, v88, v162
	v_cvt_pk_bf16_f32 v13, v90, v200
	v_cvt_pk_bf16_f32 v80, v80, v0
	v_cvt_pk_bf16_f32 v81, v82, v250
	v_cvt_pk_bf16_f32 v82, v83, v226
	v_cvt_pk_bf16_f32 v83, v84, v104
	v_cvt_pk_bf16_f32 v84, v85, v106
	v_cvt_pk_bf16_f32 v85, v87, v160
	v_cvt_pk_bf16_f32 v86, v89, v108
	v_cvt_pk_bf16_f32 v87, v91, v110
	v_add_f32_e32 v14, v14, v0
	v_add_f32_e32 v15, v15, v1
	v_add_u32_e32 v100, s36, v220
	v_add_f32_e32 v251, v14, v15
	v_add_f32_e32 v14, v248, v250
	v_add_f32_e32 v15, v249, v251
	s_waitcnt lgkmcnt(3)
	v_mfma_f32_32x32x16_bf16 v[64:79], v[236:239], v[6:9], v[64:79]
	v_add_f32_e32 v227, v14, v15
	v_add_f32_e32 v14, v224, v226
	v_add_f32_e32 v15, v225, v227
	ds_read_b128 v[88:91], v100
	ds_read_b128 v[92:95], v100 offset:4096
	ds_read_b128 v[96:99], v100 offset:8192
	ds_read_b128 v[100:103], v100 offset:12288
	v_add_f32_e32 v105, v14, v15
	v_add_f32_e32 v14, v196, v104
	v_add_f32_e32 v15, v197, v105
	s_waitcnt lgkmcnt(6)
	v_mfma_f32_32x32x16_bf16 v[48:63], v[240:243], v[6:9], v[48:63]
	v_add_f32_e32 v107, v14, v15
	v_add_f32_e32 v14, v198, v106
	v_add_f32_e32 v15, v199, v107
	s_nop 0
	v_add_f32_e32 v161, v14, v15
	v_add_f32_e32 v14, v164, v160
	v_add_f32_e32 v15, v165, v161
	s_waitcnt lgkmcnt(5)
	v_mfma_f32_32x32x16_bf16 v[32:47], v[228:231], v[6:9], v[32:47]
	v_add_f32_e32 v109, v14, v15
	v_add_f32_e32 v14, v162, v108
	v_add_f32_e32 v15, v163, v109
	s_nop 0
	v_add_f32_e32 v111, v14, v15
	v_add_f32_e32 v14, v200, v110
	v_add_f32_e32 v15, v201, v111
	s_waitcnt lgkmcnt(4)
	v_mfma_f32_32x32x16_bf16 v[16:31], v[244:247], v[6:9], v[16:31]
	v_add_f32_e32 v0, v14, v15
	v_add_f32_e32 v6, v184, v0
	s_waitcnt lgkmcnt(3)
	v_mfma_f32_32x32x16_bf16 v[64:79], v[88:91], v[10:13], v[64:79]
	v_add_u32_e32 v0, s36, v221
	s_waitcnt lgkmcnt(2)
	v_mfma_f32_32x32x16_bf16 v[48:63], v[92:95], v[10:13], v[48:63]
	s_waitcnt lgkmcnt(1)
	v_mfma_f32_32x32x16_bf16 v[32:47], v[96:99], v[10:13], v[32:47]
	ds_read_b128 v[88:91], v0
	ds_read_b128 v[92:95], v0 offset:4096
	ds_read_b128 v[96:99], v0 offset:8192
	ds_read_b128 v[104:107], v0 offset:12288
	s_waitcnt lgkmcnt(4)
	v_mfma_f32_32x32x16_bf16 v[16:31], v[100:103], v[10:13], v[16:31]
	v_add_u32_e32 v0, s36, v222
	ds_read_b128 v[8:11], v0
	ds_read_b128 v[12:15], v0 offset:4096
	s_waitcnt lgkmcnt(5)
	v_mfma_f32_32x32x16_bf16 v[64:79], v[88:91], v[80:83], v[64:79]
	ds_read_b128 v[88:91], v0 offset:8192
	ds_read_b128 v[100:103], v0 offset:12288
	v_max_f32_e32 v0, v113, v113
	v_max_f32_e32 v7, v129, v129
	v_max_f32_e32 v0, v0, v7
	v_max3_f32 v7, v112, v128, v114
	v_max3_f32 v0, v0, v115, v131
	v_max3_f32 v7, v7, v130, v116
	v_max3_f32 v0, v0, v117, v133
	s_waitcnt lgkmcnt(6)
	v_mfma_f32_32x32x16_bf16 v[48:63], v[92:95], v[80:83], v[48:63]
	v_max3_f32 v7, v7, v132, v118
	v_max3_f32 v0, v0, v119, v135
	v_max3_f32 v7, v7, v134, v120
	v_max3_f32 v0, v0, v121, v137
	v_max3_f32 v7, v7, v136, v122
	v_max3_f32 v0, v0, v123, v139
	v_max3_f32 v7, v7, v138, v124
	s_waitcnt lgkmcnt(5)
	v_mfma_f32_32x32x16_bf16 v[32:47], v[96:99], v[80:83], v[32:47]
	v_max3_f32 v0, v0, v125, v141
	v_max3_f32 v7, v7, v140, v126
	v_max3_f32 v0, v0, v127, v143
	v_max3_f32 v0, v7, v142, v0
	v_mov_b32_e32 v7, v0
	s_nop 1
	v_permlane32_swap_b32_e32 v0, v7
	s_waitcnt lgkmcnt(4)
	v_mfma_f32_32x32x16_bf16 v[16:31], v[104:107], v[80:83], v[16:31]
	s_waitcnt lgkmcnt(3)
	v_mfma_f32_32x32x16_bf16 v[64:79], v[8:11], v[84:87], v[64:79]
	v_max_f32_e32 v7, v7, v7
	v_max_f32_e32 v0, v0, v0
	v_max_f32_e32 v0, v0, v7
	v_cmp_lt_f32_e32 vcc, s93, v0
	s_waitcnt lgkmcnt(2)
	v_mfma_f32_32x32x16_bf16 v[48:63], v[12:15], v[84:87], v[48:63]
	s_waitcnt lgkmcnt(1)
	v_mfma_f32_32x32x16_bf16 v[32:47], v[88:91], v[84:87], v[32:47]
	s_waitcnt lgkmcnt(0)
	v_mfma_f32_32x32x16_bf16 v[16:31], v[100:103], v[84:87], v[16:31]
	s_cbranch_vccz .LBB0_591
	v_max_f32_e32 v0, v0, v0
	v_max_f32_e32 v7, 0, v0
	v_exp_f32_e64 v0, -v7
	v_add_f32_e32 v169, v169, v7
	v_sub_f32_e32 v127, v127, v7
	v_sub_f32_e32 v126, v126, v7
	v_pk_mul_f32 v[78:79], v[78:79], v[0:1] op_sel_hi:[1,0]
	v_pk_mul_f32 v[76:77], v[76:77], v[0:1] op_sel_hi:[1,0]
	v_pk_mul_f32 v[74:75], v[74:75], v[0:1] op_sel_hi:[1,0]
	v_pk_mul_f32 v[72:73], v[72:73], v[0:1] op_sel_hi:[1,0]
	v_pk_mul_f32 v[70:71], v[70:71], v[0:1] op_sel_hi:[1,0]
	v_pk_mul_f32 v[68:69], v[68:69], v[0:1] op_sel_hi:[1,0]
	v_pk_mul_f32 v[66:67], v[66:67], v[0:1] op_sel_hi:[1,0]
	v_pk_mul_f32 v[64:65], v[64:65], v[0:1] op_sel_hi:[1,0]
	v_pk_mul_f32 v[62:63], v[62:63], v[0:1] op_sel_hi:[1,0]
	v_pk_mul_f32 v[60:61], v[60:61], v[0:1] op_sel_hi:[1,0]
	v_pk_mul_f32 v[58:59], v[58:59], v[0:1] op_sel_hi:[1,0]
	v_pk_mul_f32 v[56:57], v[56:57], v[0:1] op_sel_hi:[1,0]
	v_pk_mul_f32 v[54:55], v[54:55], v[0:1] op_sel_hi:[1,0]
	v_pk_mul_f32 v[52:53], v[52:53], v[0:1] op_sel_hi:[1,0]
	v_pk_mul_f32 v[50:51], v[50:51], v[0:1] op_sel_hi:[1,0]
	v_pk_mul_f32 v[48:49], v[48:49], v[0:1] op_sel_hi:[1,0]
	v_pk_mul_f32 v[46:47], v[0:1], v[46:47] op_sel_hi:[0,1]
	v_pk_mul_f32 v[44:45], v[0:1], v[44:45] op_sel_hi:[0,1]
	v_pk_mul_f32 v[42:43], v[0:1], v[42:43] op_sel_hi:[0,1]
	v_pk_mul_f32 v[40:41], v[0:1], v[40:41] op_sel_hi:[0,1]
	v_pk_mul_f32 v[38:39], v[0:1], v[38:39] op_sel_hi:[0,1]
	v_pk_mul_f32 v[36:37], v[0:1], v[36:37] op_sel_hi:[0,1]
	v_pk_mul_f32 v[34:35], v[0:1], v[34:35] op_sel_hi:[0,1]
	v_pk_mul_f32 v[32:33], v[0:1], v[32:33] op_sel_hi:[0,1]
	v_pk_mul_f32 v[30:31], v[0:1], v[30:31] op_sel_hi:[0,1]
	v_pk_mul_f32 v[28:29], v[0:1], v[28:29] op_sel_hi:[0,1]
	v_pk_mul_f32 v[26:27], v[0:1], v[26:27] op_sel_hi:[0,1]
	v_pk_mul_f32 v[24:25], v[0:1], v[24:25] op_sel_hi:[0,1]
	v_pk_mul_f32 v[22:23], v[0:1], v[22:23] op_sel_hi:[0,1]
	v_pk_mul_f32 v[20:21], v[0:1], v[20:21] op_sel_hi:[0,1]
	v_pk_mul_f32 v[18:19], v[0:1], v[18:19] op_sel_hi:[0,1]
	v_pk_mul_f32 v[16:17], v[0:1], v[16:17] op_sel_hi:[0,1]
	v_sub_f32_e32 v125, v125, v7
	v_sub_f32_e32 v124, v124, v7
	v_sub_f32_e32 v123, v123, v7
	v_sub_f32_e32 v122, v122, v7
	v_sub_f32_e32 v121, v121, v7
	v_sub_f32_e32 v120, v120, v7
	v_sub_f32_e32 v119, v119, v7
	v_sub_f32_e32 v118, v118, v7
	v_sub_f32_e32 v117, v117, v7
	v_sub_f32_e32 v116, v116, v7
	v_sub_f32_e32 v115, v115, v7
	v_sub_f32_e32 v114, v114, v7
	v_sub_f32_e32 v113, v113, v7
	v_sub_f32_e32 v112, v112, v7
	v_sub_f32_e32 v143, v143, v7
	v_sub_f32_e32 v142, v142, v7
	v_sub_f32_e32 v141, v141, v7
	v_sub_f32_e32 v140, v140, v7
	v_sub_f32_e32 v139, v139, v7
	v_sub_f32_e32 v138, v138, v7
	v_sub_f32_e32 v137, v137, v7
	v_sub_f32_e32 v136, v136, v7
	v_sub_f32_e32 v135, v135, v7
	v_sub_f32_e32 v134, v134, v7
	v_sub_f32_e32 v133, v133, v7
	v_sub_f32_e32 v132, v132, v7
	v_sub_f32_e32 v131, v131, v7
	v_sub_f32_e32 v130, v130, v7
	v_sub_f32_e32 v129, v129, v7
	v_sub_f32_e32 v128, v128, v7
	v_mul_f32_e32 v6, v6, v0
.LBB0_591:
	v_cvt_f32_u32_e32 v96, s28
	v_sub_f32_e32 v96, v96, v205
	v_fma_f32 v96, v166, v96, -v169
	v_add_f32_e32 v80, v168, v96
	v_add_f32_e32 v81, v166, v80
	v_add_f32_e32 v82, v167, v80
	v_add_f32_e32 v83, v186, v80
	v_add_f32_e32 v84, v187, v80
	v_add_f32_e32 v85, v166, v84
	v_add_f32_e32 v86, v167, v84
	v_add_f32_e32 v87, v186, v84
	v_add_f32_e32 v88, v187, v84
	v_add_f32_e32 v89, v166, v88
	v_add_f32_e32 v90, v167, v88
	v_add_f32_e32 v91, v186, v88
	v_add_f32_e32 v92, v187, v88
	v_add_f32_e32 v93, v166, v92
	v_add_f32_e32 v94, v167, v92
	v_add_f32_e32 v95, v186, v92
	v_add_f32_e32 v97, v166, v96
	v_add_f32_e32 v98, v167, v96
	v_add_f32_e32 v99, v186, v96
	v_add_f32_e32 v100, v187, v96
	v_add_f32_e32 v101, v166, v100
	v_add_f32_e32 v102, v167, v100
	v_add_f32_e32 v103, v186, v100
	v_add_f32_e32 v104, v187, v100
	v_add_f32_e32 v105, v166, v104
	v_add_f32_e32 v106, v167, v104
	v_add_f32_e32 v107, v186, v104
	v_add_f32_e32 v108, v187, v104
	v_add_f32_e32 v109, v166, v108
	v_add_f32_e32 v110, v167, v108
	v_add_f32_e32 v111, v186, v108
	s_mov_b64 s[42:43], -1
	s_and_b64 vcc, exec, s[12:13]
	s_cbranch_vccnz .LBB0_603
	s_andn2_b64 vcc, exec, s[42:43]
	s_cbranch_vccz .LBB0_604

.LBB0_595:
	s_add_i32 s36, s21, 0xffff4000
	s_and_b32 s36, s36, 0x8000
	s_add_i32 s36, s36, 0
	v_add_u32_e32 v0, s36, v210
	ds_read_b128 v[2:5], v0
	ds_read_b128 v[8:11], v0 offset:8192
	v_add_u32_e32 v7, s36, v211
	ds_read_b128 v[12:15], v7
	ds_read_b128 v[224:227], v7 offset:8192
	s_waitcnt lgkmcnt(3)
	v_mfma_f32_32x32x16_bf16 v[96:111], v[2:5], v[144:147], v[96:111]
	v_add_u32_e32 v0, s36, v212
	v_exp_f32_e32 v7, v112
	v_exp_f32_e32 v112, v128
	v_exp_f32_e32 v160, v129
	v_exp_f32_e32 v116, v116
	v_exp_f32_e32 v128, v132
	v_exp_f32_e32 v132, v115
	s_waitcnt lgkmcnt(2)
	v_mfma_f32_32x32x16_bf16 v[80:95], v[8:11], v[144:147], v[80:95]
	ds_read_b128 v[2:5], v0
	ds_read_b128 v[8:11], v0 offset:8192
	v_add_u32_e32 v0, s36, v213
	v_exp_f32_e32 v162, v131
	v_exp_f32_e32 v115, v134
	v_exp_f32_e32 v134, v117
	v_exp_f32_e32 v164, v133
	v_exp_f32_e32 v198, v119
	s_waitcnt lgkmcnt(3)
	v_mfma_f32_32x32x16_bf16 v[96:111], v[12:15], v[148:151], v[96:111]
	ds_read_b128 v[12:15], v0
	ds_read_b128 v[228:231], v0 offset:8192
	v_add_u32_e32 v0, s30, v204
	ds_read_b128 v[232:235], v0
	ds_read_b128 v[236:239], v0 offset:4096
	v_exp_f32_e32 v117, v136
	v_exp_f32_e32 v196, v135
	v_exp_f32_e32 v136, v121
	v_exp_f32_e32 v200, v137
	s_waitcnt lgkmcnt(6)
	v_mfma_f32_32x32x16_bf16 v[80:95], v[224:227], v[148:151], v[80:95]
	ds_read_b128 v[224:227], v0 offset:8192
	ds_read_b128 v[240:243], v0 offset:12288
	v_exp_f32_e32 v0, v113
	v_exp_f32_e32 v113, v114
	v_exp_f32_e32 v114, v130
	v_exp_f32_e32 v244, v139
	v_exp_f32_e32 v119, v140
	v_exp_f32_e32 v140, v125
	s_waitcnt lgkmcnt(7)
	v_mfma_f32_32x32x16_bf16 v[96:111], v[2:5], v[152:155], v[96:111]
	v_exp_f32_e32 v5, v118
	v_exp_f32_e32 v118, v138
	v_exp_f32_e32 v138, v123
	v_exp_f32_e32 v246, v141
	v_exp_f32_e32 v248, v143
	v_add_f32_e32 v161, v112, v7
	v_add_f32_e32 v163, v114, v113
	s_waitcnt lgkmcnt(6)
	v_mfma_f32_32x32x16_bf16 v[80:95], v[8:11], v[152:155], v[80:95]
	v_add_f32_e32 v165, v128, v116
	v_add_f32_e32 v197, v115, v5
	v_cvt_pk_bf16_f32 v2, v7, v0
	v_cvt_pk_bf16_f32 v3, v113, v132
	v_cvt_pk_bf16_f32 v4, v116, v134
	v_cvt_pk_bf16_f32 v5, v5, v198
	v_cvt_pk_bf16_f32 v113, v118, v244
	s_waitcnt lgkmcnt(5)
	v_mfma_f32_32x32x16_bf16 v[96:111], v[12:15], v[156:159], v[96:111]
	v_exp_f32_e32 v12, v120
	v_exp_f32_e32 v13, v122
	v_exp_f32_e32 v14, v124
	v_exp_f32_e32 v15, v126
	v_exp_f32_e32 v120, v142
	v_exp_f32_e32 v142, v127
	v_add_f32_e32 v201, v117, v12
	s_waitcnt lgkmcnt(4)
	v_mfma_f32_32x32x16_bf16 v[80:95], v[228:231], v[156:159], v[80:95]
	v_add_f32_e32 v245, v118, v13
	v_add_f32_e32 v247, v119, v14
	v_add_f32_e32 v249, v120, v15
	v_cvt_pk_bf16_f32 v8, v12, v136
	v_cvt_pk_bf16_f32 v9, v13, v138
	v_cvt_pk_bf16_f32 v10, v14, v140
	v_cvt_pk_bf16_f32 v11, v15, v142
	v_cvt_pk_bf16_f32 v12, v112, v160
	v_cvt_pk_bf16_f32 v13, v114, v162
	v_cvt_pk_bf16_f32 v14, v128, v164
	v_cvt_pk_bf16_f32 v15, v115, v196
	v_cvt_pk_bf16_f32 v112, v117, v200
	v_cvt_pk_bf16_f32 v114, v119, v246
	v_cvt_pk_bf16_f32 v115, v120, v248
	v_add_f32_e32 v160, v160, v0
	v_add_f32_e32 v161, v161, v1
	v_add_u32_e32 v7, s30, v220
	v_add_f32_e32 v161, v160, v161
	v_add_f32_e32 v160, v160, v160
	v_mov_b32_e32 v133, v161
	v_add_f32_e32 v132, v162, v132
	v_add_f32_e32 v133, v163, v133
	s_waitcnt lgkmcnt(3)
	v_mfma_f32_32x32x16_bf16 v[64:79], v[232:235], v[2:5], v[64:79]
	v_add_f32_e32 v135, v132, v133
	v_add_f32_e32 v132, v164, v134
	v_add_f32_e32 v133, v165, v135
	ds_read_b128 v[116:119], v7
	ds_read_b128 v[120:123], v7 offset:4096
	ds_read_b128 v[124:127], v7 offset:8192
	ds_read_b128 v[128:131], v7 offset:12288
	v_add_f32_e32 v199, v132, v133
	v_add_f32_e32 v132, v196, v198
	v_add_f32_e32 v133, v197, v199
	s_waitcnt lgkmcnt(6)
	v_mfma_f32_32x32x16_bf16 v[48:63], v[236:239], v[2:5], v[48:63]
	v_add_f32_e32 v137, v132, v133
	v_add_f32_e32 v132, v200, v136
	v_add_f32_e32 v133, v201, v137
	s_nop 0
	v_add_f32_e32 v139, v132, v133
	v_add_f32_e32 v132, v244, v138
	v_add_f32_e32 v133, v245, v139
	s_waitcnt lgkmcnt(5)
	v_mfma_f32_32x32x16_bf16 v[32:47], v[224:227], v[2:5], v[32:47]
	v_add_f32_e32 v141, v132, v133
	v_add_f32_e32 v132, v246, v140
	v_add_f32_e32 v133, v247, v141
	s_nop 0
	v_add_f32_e32 v143, v132, v133
	v_add_f32_e32 v132, v248, v142
	v_add_f32_e32 v133, v249, v143
	s_waitcnt lgkmcnt(4)
	v_mfma_f32_32x32x16_bf16 v[16:31], v[240:243], v[2:5], v[16:31]
	v_add_f32_e32 v0, v132, v133
	v_add_f32_e32 v184, v6, v0
	s_waitcnt lgkmcnt(3)
	v_mfma_f32_32x32x16_bf16 v[64:79], v[116:119], v[8:11], v[64:79]
	v_add_u32_e32 v0, s30, v221
	s_waitcnt lgkmcnt(2)
	v_mfma_f32_32x32x16_bf16 v[48:63], v[120:123], v[8:11], v[48:63]
	s_waitcnt lgkmcnt(1)
	v_mfma_f32_32x32x16_bf16 v[32:47], v[124:127], v[8:11], v[32:47]
	ds_read_b128 v[2:5], v0
	ds_read_b128 v[116:119], v0 offset:4096
	ds_read_b128 v[120:123], v0 offset:8192
	ds_read_b128 v[124:127], v0 offset:12288
	s_waitcnt lgkmcnt(4)
	v_mfma_f32_32x32x16_bf16 v[16:31], v[128:131], v[8:11], v[16:31]
	v_add_u32_e32 v0, s30, v222
	ds_read_b128 v[6:9], v0
	ds_read_b128 v[128:131], v0 offset:4096
	s_waitcnt lgkmcnt(5)
	v_mfma_f32_32x32x16_bf16 v[64:79], v[2:5], v[12:15], v[64:79]
	ds_read_b128 v[2:5], v0 offset:8192
	ds_read_b128 v[132:135], v0 offset:12288
	v_max_f32_e32 v0, v97, v97
	v_max_f32_e32 v10, v81, v81
	v_max_f32_e32 v0, v0, v10
	v_max3_f32 v10, v96, v80, v98
	v_max3_f32 v0, v0, v99, v83
	v_max3_f32 v10, v10, v82, v100
	v_max3_f32 v0, v0, v101, v85
	s_waitcnt lgkmcnt(6)
	v_mfma_f32_32x32x16_bf16 v[48:63], v[116:119], v[12:15], v[48:63]
	v_max3_f32 v10, v10, v84, v102
	v_max3_f32 v0, v0, v103, v87
	v_max3_f32 v10, v10, v86, v104
	v_max3_f32 v0, v0, v105, v89
	v_max3_f32 v10, v10, v88, v106
	v_max3_f32 v0, v0, v107, v91
	v_max3_f32 v10, v10, v90, v108
	s_waitcnt lgkmcnt(5)
	v_mfma_f32_32x32x16_bf16 v[32:47], v[120:123], v[12:15], v[32:47]
	v_max3_f32 v0, v0, v109, v93
	v_max3_f32 v10, v10, v92, v110
	v_max3_f32 v0, v0, v111, v95
	v_max3_f32 v0, v10, v94, v0
	v_mov_b32_e32 v10, v0
	s_nop 1
	v_permlane32_swap_b32_e32 v0, v10
	s_waitcnt lgkmcnt(4)
	v_mfma_f32_32x32x16_bf16 v[16:31], v[124:127], v[12:15], v[16:31]
	s_waitcnt lgkmcnt(3)
	v_mfma_f32_32x32x16_bf16 v[64:79], v[6:9], v[112:115], v[64:79]
	v_max_f32_e32 v0, v0, v0
	s_waitcnt lgkmcnt(2)
	v_mfma_f32_32x32x16_bf16 v[48:63], v[128:131], v[112:115], v[48:63]
	s_waitcnt lgkmcnt(1)
	v_mfma_f32_32x32x16_bf16 v[32:47], v[2:5], v[112:115], v[32:47]
	v_max_f32_e32 v2, v10, v10
	v_max_f32_e32 v0, v0, v2
	v_cmp_lt_f32_e32 vcc, s93, v0
	s_waitcnt lgkmcnt(0)
	v_mfma_f32_32x32x16_bf16 v[16:31], v[132:135], v[112:115], v[16:31]
	s_cbranch_vccz .LBB0_597
	v_max_f32_e32 v0, v0, v0
	v_max_f32_e32 v2, 0, v0
	v_exp_f32_e64 v0, -v2
	v_add_f32_e32 v169, v169, v2
	v_sub_f32_e32 v111, v111, v2
	v_sub_f32_e32 v110, v110, v2
	v_pk_mul_f32 v[78:79], v[78:79], v[0:1] op_sel_hi:[1,0]
	v_pk_mul_f32 v[76:77], v[76:77], v[0:1] op_sel_hi:[1,0]
	v_pk_mul_f32 v[74:75], v[74:75], v[0:1] op_sel_hi:[1,0]
	v_pk_mul_f32 v[72:73], v[72:73], v[0:1] op_sel_hi:[1,0]
	v_pk_mul_f32 v[70:71], v[70:71], v[0:1] op_sel_hi:[1,0]
	v_pk_mul_f32 v[68:69], v[68:69], v[0:1] op_sel_hi:[1,0]
	v_pk_mul_f32 v[66:67], v[66:67], v[0:1] op_sel_hi:[1,0]
	v_pk_mul_f32 v[64:65], v[64:65], v[0:1] op_sel_hi:[1,0]
	v_pk_mul_f32 v[62:63], v[62:63], v[0:1] op_sel_hi:[1,0]
	v_pk_mul_f32 v[60:61], v[60:61], v[0:1] op_sel_hi:[1,0]
	v_pk_mul_f32 v[58:59], v[58:59], v[0:1] op_sel_hi:[1,0]
	v_pk_mul_f32 v[56:57], v[56:57], v[0:1] op_sel_hi:[1,0]
	v_pk_mul_f32 v[54:55], v[54:55], v[0:1] op_sel_hi:[1,0]
	v_pk_mul_f32 v[52:53], v[52:53], v[0:1] op_sel_hi:[1,0]
	v_pk_mul_f32 v[50:51], v[50:51], v[0:1] op_sel_hi:[1,0]
	v_pk_mul_f32 v[48:49], v[48:49], v[0:1] op_sel_hi:[1,0]
	v_pk_mul_f32 v[46:47], v[0:1], v[46:47] op_sel_hi:[0,1]
	v_pk_mul_f32 v[44:45], v[0:1], v[44:45] op_sel_hi:[0,1]
	v_pk_mul_f32 v[42:43], v[0:1], v[42:43] op_sel_hi:[0,1]
	v_pk_mul_f32 v[40:41], v[0:1], v[40:41] op_sel_hi:[0,1]
	v_pk_mul_f32 v[38:39], v[0:1], v[38:39] op_sel_hi:[0,1]
	v_pk_mul_f32 v[36:37], v[0:1], v[36:37] op_sel_hi:[0,1]
	v_pk_mul_f32 v[34:35], v[0:1], v[34:35] op_sel_hi:[0,1]
	v_pk_mul_f32 v[32:33], v[0:1], v[32:33] op_sel_hi:[0,1]
	v_pk_mul_f32 v[30:31], v[0:1], v[30:31] op_sel_hi:[0,1]
	v_pk_mul_f32 v[28:29], v[0:1], v[28:29] op_sel_hi:[0,1]
	v_pk_mul_f32 v[26:27], v[0:1], v[26:27] op_sel_hi:[0,1]
	v_pk_mul_f32 v[24:25], v[0:1], v[24:25] op_sel_hi:[0,1]
	v_pk_mul_f32 v[22:23], v[0:1], v[22:23] op_sel_hi:[0,1]
	v_pk_mul_f32 v[20:21], v[0:1], v[20:21] op_sel_hi:[0,1]
	v_pk_mul_f32 v[18:19], v[0:1], v[18:19] op_sel_hi:[0,1]
	v_pk_mul_f32 v[16:17], v[0:1], v[16:17] op_sel_hi:[0,1]
	v_sub_f32_e32 v109, v109, v2
	v_sub_f32_e32 v108, v108, v2
	v_sub_f32_e32 v107, v107, v2
	v_sub_f32_e32 v106, v106, v2
	v_sub_f32_e32 v105, v105, v2
	v_sub_f32_e32 v104, v104, v2
	v_sub_f32_e32 v103, v103, v2
	v_sub_f32_e32 v102, v102, v2
	v_sub_f32_e32 v101, v101, v2
	v_sub_f32_e32 v100, v100, v2
	v_sub_f32_e32 v99, v99, v2
	v_sub_f32_e32 v98, v98, v2
	v_sub_f32_e32 v97, v97, v2
	v_sub_f32_e32 v96, v96, v2
	v_sub_f32_e32 v95, v95, v2
	v_sub_f32_e32 v94, v94, v2
	v_sub_f32_e32 v93, v93, v2
	v_sub_f32_e32 v92, v92, v2
	v_sub_f32_e32 v91, v91, v2
	v_sub_f32_e32 v90, v90, v2
	v_sub_f32_e32 v89, v89, v2
	v_sub_f32_e32 v88, v88, v2
	v_sub_f32_e32 v87, v87, v2
	v_sub_f32_e32 v86, v86, v2
	v_sub_f32_e32 v85, v85, v2
	v_sub_f32_e32 v84, v84, v2
	v_sub_f32_e32 v83, v83, v2
	v_sub_f32_e32 v82, v82, v2
	v_sub_f32_e32 v81, v81, v2
	v_sub_f32_e32 v80, v80, v2
	v_mul_f32_e32 v184, v184, v0
.LBB0_597:
	s_add_i32 s30, s28, 64
	v_cvt_f32_u32_e32 v112, s30
	v_sub_f32_e32 v112, v112, v205
	v_fma_f32 v112, v166, v112, -v169
	v_add_f32_e32 v128, v168, v112
	v_add_f32_e32 v129, v166, v128
	v_add_f32_e32 v130, v167, v128
	v_add_f32_e32 v131, v186, v128
	v_add_f32_e32 v132, v187, v128
	v_add_f32_e32 v133, v166, v132
	v_add_f32_e32 v134, v167, v132
	v_add_f32_e32 v135, v186, v132
	v_add_f32_e32 v136, v187, v132
	v_add_f32_e32 v137, v166, v136
	v_add_f32_e32 v138, v167, v136
	v_add_f32_e32 v139, v186, v136
	v_add_f32_e32 v140, v187, v136
	v_add_f32_e32 v141, v166, v140
	v_add_f32_e32 v142, v167, v140
	v_add_f32_e32 v143, v186, v140
	v_add_f32_e32 v113, v166, v112
	v_add_f32_e32 v114, v167, v112
	v_add_f32_e32 v115, v186, v112
	v_add_f32_e32 v116, v187, v112
	v_add_f32_e32 v117, v166, v116
	v_add_f32_e32 v118, v167, v116
	v_add_f32_e32 v119, v186, v116
	v_add_f32_e32 v120, v187, v116
	v_add_f32_e32 v121, v166, v120
	v_add_f32_e32 v122, v167, v120
	v_add_f32_e32 v123, v186, v120
	v_add_f32_e32 v124, v187, v120
	v_add_f32_e32 v125, v166, v124
	v_add_f32_e32 v126, v167, v124
	v_add_f32_e32 v127, v186, v124
	s_mov_b64 s[42:43], -1
	s_and_b64 vcc, exec, s[12:13]
	s_cbranch_vccz .LBB0_599
	s_waitcnt vmcnt(0) lgkmcnt(0)
	s_barrier
	s_mov_b64 s[42:43], 0
